# v47 + P4 and P6 epilogues staggered the same way (ALIGN_EPI barrier only at the last unit)
# speedup vs baseline: 1.0261x; 1.0001x over previous
.Lpeel_done_2:
	v_readlane_b32 s44, v254, 27
	v_readlane_b32 s45, v254, 28
	s_andn2_b64 s[44:45], s[44:45], s[40:41]
	s_and_b64 vcc, exec, s[44:45]
	s_cbranch_vccz .LBB0_2028
	s_barrier
	s_cmp_lt_i32 s14, 0
	s_mov_b64 s[44:45], -1
	s_cbranch_scc1 .LBB0_2029

.LBB0_2047:
	v_readlane_b32 s4, v254, 58
	v_readlane_b32 s5, v254, 59
	s_and_b64 vcc, exec, s[4:5]
	s_cbranch_vccnz .LBB0_2005
	s_nop 0
	s_branch .LBB0_2005

.Lpeel_done_4:
	v_readlane_b32 s44, v254, 27
	v_readlane_b32 s45, v254, 28
	s_andn2_b64 s[44:45], s[44:45], s[38:39]
	s_and_b64 vcc, exec, s[44:45]
	s_cbranch_vccz .LBB0_2461
	s_barrier
	s_cmp_lt_i32 s10, 0
	s_mov_b64 s[44:45], -1
	s_cbranch_scc1 .LBB0_2462

.LBB0_2464:
	v_readlane_b32 s38, v254, 58
	v_readlane_b32 s39, v254, 59
	s_and_b64 vcc, exec, s[38:39]
	s_cbranch_vccnz .LBB0_2438
	s_nop 0
	s_branch .LBB0_2438
